# v6: v3 + ALiBi bias in diff-attention via v_fma_f32 with abs/neg source modifiers instead of v_and + v_pk_fma (bit-identical)
# speedup vs baseline: 1.0098x; 1.0071x over previous
; #define LAS __attribute__((address_space(3)))
; __device__ __forceinline__ float max3f(float a, float b, float c) { float r; asm("v_max3_f32 %0, %1, %2, %3" : "=v"(r) : "v"(a), "v"(b), "v"(c)); return r; }
; template <int DQK, int DV, bool BIAS> ...
;     ...
;         const LAS unsigned char* kb = lds + buf * KBUF + r32 * KP + hi * 16;
; #pragma unroll
;         for (int ks = 0; ks < NKS; ++ks) {
;             const bf16x8 k0 = *(const LAS bf16x8*)(kb + ks * 32), k1 = *(const LAS bf16x8*)(kb + 32 * KP + ks * 32);
;             if (ks == 0) { p0 = __builtin_amdgcn_mfma_f32_32x32x16_bf16(k0, qf[0], negm, 0, 0, 0); p1 = __builtin_amdgcn_mfma_f32_32x32x16_bf16(k1, qf[0], negm, 0, 0, 0); }
;             else { p0 = __builtin_amdgcn_mfma_f32_32x32x16_bf16(k0, qf[ks], p0, 0, 0, 0); p1 = __builtin_amdgcn_mfma_f32_32x32x16_bf16(k1, qf[ks], p1, 0, 0, 0); }
;         }
;         if (BIAS) {
;             asm volatile("s_nop 15\n\ts_nop 7" : "+v"(p0), "+v"(p1));
;             const float d0 = qp - (float)(t * 64 + 4 * hi);
; #pragma unroll
;             for (int r = 0; r < 16; ++r) { const float dk = d0 - (float)((r & 3) + 8 * (r >> 2)); p0[r] = p0[r] - sl2 * fabsf(dk); p1[r] = p1[r] - sl2 * fabsf(dk - 32.f); }
;         } else {
;             asm volatile("s_nop 15\n\ts_nop 7" : "+v"(p0), "+v"(p1));
;         }
;         float mxa = max3f(p0[0], p0[1], p1[0]), mxb = max3f(p0[2], p0[3], p1[1]); mxa = max3f(mxa, p1[2], p1[3]);
; #pragma unroll
;         for (int r = 4; r < 16; r += 4) { mxa = max3f(mxa, p0[r], p0[r + 1]); mxb = max3f(mxb, p0[r + 2], p0[r + 3]); mxa = max3f(mxa, p1[r], p1[r + 1]); mxb = max3f(mxb, p1[r + 2], p1[r + 3]); }
;         float mx = fmaxf(mxa, mxb);
;         if (__any(mx > 8.f)) {
.LBB0_578:
	ds_read_b128 v[82:85], v175
	ds_read_b128 v[152:155], v175 offset:32
	ds_read_b128 v[156:159], v175 offset:4608
	ds_read_b128 v[160:163], v175 offset:4640
	v_cvt_f32_u32_e32 v150, v173
	s_waitcnt lgkmcnt(3)
	v_mfma_f32_32x32x16_bf16 v[98:113], v[82:85], v[114:117], v[66:81]
	v_sub_f32_e32 v178, v172, v150
	v_add_f32_e32 v179, -1.0, v178
	s_waitcnt lgkmcnt(1)
	v_mfma_f32_32x32x16_bf16 v[82:97], v[156:159], v[114:117], v[66:81]
	v_mfma_f32_32x32x16_bf16 v[98:113], v[152:155], v[118:121], v[98:113]
	ds_read_b128 v[152:155], v175 offset:64
	ds_read_b128 v[156:159], v175 offset:96
	s_waitcnt lgkmcnt(2)
	v_mfma_f32_32x32x16_bf16 v[82:97], v[160:163], v[118:121], v[82:97]
	s_waitcnt lgkmcnt(1)
	v_mfma_f32_32x32x16_bf16 v[98:113], v[152:155], v[122:125], v[98:113]
	ds_read_b128 v[152:155], v175 offset:4672
	ds_read_b128 v[160:163], v175 offset:4704
	s_waitcnt lgkmcnt(1)
	v_mfma_f32_32x32x16_bf16 v[82:97], v[152:155], v[122:125], v[82:97]
	v_and_b32_e32 v152, 0x7fffffff, v178
	v_and_b32_e32 v153, 0x7fffffff, v179
	v_mfma_f32_32x32x16_bf16 v[98:113], v[156:159], v[126:129], v[98:113]
	s_waitcnt lgkmcnt(0)
	v_mfma_f32_32x32x16_bf16 v[82:97], v[160:163], v[126:129], v[82:97]
	s_nop 15
	s_nop 7
	s_nop 9
	v_pk_fma_f32 v[156:157], v[142:143], v[152:153], v[98:99] neg_lo:[1,0,0] neg_hi:[1,0,0]
	v_pk_add_f32 v[98:99], v[178:179], s[8:9] op_sel_hi:[1,0]
	s_nop 0
	v_fma_f32 v99, -v143, |v99|, v83
	v_fma_f32 v98, -v142, |v98|, v82
	v_pk_add_f32 v[82:83], v[178:179], s[10:11] op_sel_hi:[0,1]
	v_fma_f32 v161, -v143, |v83|, v101
	v_fma_f32 v160, -v142, |v82|, v100
	v_pk_add_f32 v[82:83], v[82:83], s[8:9] op_sel_hi:[1,0]
	v_fma_f32 v153, -v143, |v83|, v85
	v_fma_f32 v152, -v142, |v82|, v84
	v_pk_add_f32 v[82:83], v[178:179], s[22:23] op_sel_hi:[0,1]
	v_fma_f32 v165, -v143, |v83|, v103
	v_fma_f32 v164, -v142, |v82|, v102
	v_pk_add_f32 v[82:83], v[82:83], s[8:9] op_sel_hi:[1,0]
	v_fma_f32 v103, -v143, |v83|, v87
	v_fma_f32 v102, -v142, |v82|, v86
	v_pk_add_f32 v[82:83], v[178:179], s[34:35] op_sel_hi:[0,1]
	v_fma_f32 v167, -v143, |v83|, v105
	v_fma_f32 v166, -v142, |v82|, v104
	v_pk_add_f32 v[82:83], v[82:83], s[8:9] op_sel_hi:[1,0]
	v_fma_f32 v155, -v143, |v83|, v89
	v_fma_f32 v154, -v142, |v82|, v88
	v_pk_add_f32 v[82:83], v[178:179], s[36:37] op_sel_hi:[0,1]
	v_fma_f32 v159, -v143, |v83|, v107
	v_fma_f32 v158, -v142, |v82|, v106
	v_pk_add_f32 v[82:83], v[82:83], s[8:9] op_sel_hi:[1,0]
	v_fma_f32 v101, -v143, |v83|, v91
	v_fma_f32 v100, -v142, |v82|, v90
	v_pk_add_f32 v[82:83], v[178:179], s[38:39] op_sel_hi:[0,1]
	v_fma_f32 v163, -v143, |v83|, v109
	v_fma_f32 v162, -v142, |v82|, v108
	v_pk_add_f32 v[82:83], v[82:83], s[8:9] op_sel_hi:[1,0]
	v_fma_f32 v105, -v143, |v83|, v93
	v_fma_f32 v104, -v142, |v82|, v92
	v_pk_add_f32 v[82:83], v[178:179], s[40:41] op_sel_hi:[0,1]
	v_fma_f32 v111, -v143, |v83|, v111
	v_fma_f32 v110, -v142, |v82|, v110
	v_pk_add_f32 v[82:83], v[82:83], s[8:9] op_sel_hi:[1,0]
	v_fma_f32 v107, -v143, |v83|, v95
	v_fma_f32 v106, -v142, |v82|, v94
	v_pk_add_f32 v[82:83], v[178:179], s[42:43] op_sel_hi:[0,1]
	v_fma_f32 v113, -v143, |v83|, v113
	v_fma_f32 v112, -v142, |v82|, v112
	v_pk_add_f32 v[82:83], v[82:83], s[8:9] op_sel_hi:[1,0]
	v_fma_f32 v109, -v143, |v83|, v97
	v_fma_f32 v108, -v142, |v82|, v96
	v_max3_f32 v82, v156, v157, v98
	v_max3_f32 v83, v160, v161, v99
	s_nop 0
	v_max3_f32 v82, v82, v152, v153
	v_max3_f32 v83, v83, v166, v167
	s_nop 0
	v_max3_f32 v82, v82, v164, v165
	v_max3_f32 v83, v83, v154, v155
	s_nop 0
	v_max3_f32 v82, v82, v102, v103
	v_max3_f32 v83, v83, v162, v163
	s_nop 0
	v_max3_f32 v82, v82, v158, v159
	v_max3_f32 v83, v83, v104, v105
	s_nop 0
	v_max3_f32 v82, v82, v100, v101
	v_max3_f32 v83, v83, v112, v113
	s_nop 0
	v_max3_f32 v82, v82, v110, v111
	v_max3_f32 v83, v83, v108, v109
	s_nop 0
	v_max3_f32 v82, v82, v106, v107
	v_max_f32_e32 v83, v83, v83
	v_max_f32_e32 v82, v82, v82
	v_max_f32_e32 v82, v82, v83
	v_cmp_lt_f32_e32 vcc, s52, v82
	s_cbranch_vccz .LBB0_580
; template <int DQK, int DV, bool BIAS> ...
;     ...
;         if (__any(mx > 8.f)) {
;             mx = fmaxf(mx, __shfl_xor(mx, 32));
;             const float dl = fmaxf(mx, 0.f); mhat += dl;
;             const float f = __builtin_amdgcn_exp2f(-dl);
; #pragma unroll
;             for (int r = 0; r < 16; ++r) { p0[r] -= dl; p1[r] -= dl; negm[r] = -mhat; }
;             l *= f;
; #pragma unroll
;             for (int d = 0; d < NDT; ++d)
; #pragma unroll
;                 for (int r = 0; r < 16; ++r) o[d][r] *= f;
;         }
	v_and_b32_e32 v67, 64, v170
	v_xor_b32_e32 v66, 32, v170
	v_add_u32_e32 v67, 64, v67
	v_cmp_lt_i32_e32 vcc, v66, v67
	s_nop 1
	v_cndmask_b32_e32 v66, v170, v66, vcc
	v_lshlrev_b32_e32 v66, 2, v66
	ds_bpermute_b32 v66, v66, v82
	s_waitcnt lgkmcnt(0)
	v_max3_f32 v67, v82, v66, 0
	v_exp_f32_e64 v66, -v67
	v_add_f32_e32 v176, v176, v67
	v_xor_b32_e32 v82, 0x80000000, v176
	v_sub_f32_e32 v98, v98, v67
	v_sub_f32_e32 v99, v99, v67
	v_sub_f32_e32 v152, v152, v67
	v_sub_f32_e32 v153, v153, v67
	v_sub_f32_e32 v102, v102, v67
	v_sub_f32_e32 v103, v103, v67
	v_sub_f32_e32 v154, v154, v67
	v_sub_f32_e32 v155, v155, v67
	v_sub_f32_e32 v100, v100, v67
	v_sub_f32_e32 v101, v101, v67
	v_sub_f32_e32 v104, v104, v67
	v_sub_f32_e32 v105, v105, v67
	v_sub_f32_e32 v106, v106, v67
	v_sub_f32_e32 v107, v107, v67
	v_sub_f32_e32 v108, v108, v67
	v_sub_f32_e32 v109, v109, v67
	v_pk_mul_f32 v[64:65], v[64:65], v[66:67] op_sel_hi:[1,0]
	v_pk_mul_f32 v[62:63], v[62:63], v[66:67] op_sel_hi:[1,0]
	v_pk_mul_f32 v[60:61], v[60:61], v[66:67] op_sel_hi:[1,0]
	v_pk_mul_f32 v[58:59], v[58:59], v[66:67] op_sel_hi:[1,0]
	v_pk_mul_f32 v[56:57], v[56:57], v[66:67] op_sel_hi:[1,0]
	v_pk_mul_f32 v[54:55], v[54:55], v[66:67] op_sel_hi:[1,0]
	v_pk_mul_f32 v[52:53], v[52:53], v[66:67] op_sel_hi:[1,0]
	v_pk_mul_f32 v[50:51], v[50:51], v[66:67] op_sel_hi:[1,0]
	v_pk_mul_f32 v[48:49], v[48:49], v[66:67] op_sel_hi:[1,0]
	v_pk_mul_f32 v[46:47], v[46:47], v[66:67] op_sel_hi:[1,0]
	v_pk_mul_f32 v[44:45], v[44:45], v[66:67] op_sel_hi:[1,0]
	v_pk_mul_f32 v[42:43], v[42:43], v[66:67] op_sel_hi:[1,0]
	v_pk_mul_f32 v[40:41], v[40:41], v[66:67] op_sel_hi:[1,0]
	v_pk_mul_f32 v[38:39], v[38:39], v[66:67] op_sel_hi:[1,0]
	v_pk_mul_f32 v[36:37], v[36:37], v[66:67] op_sel_hi:[1,0]
	v_pk_mul_f32 v[34:35], v[34:35], v[66:67] op_sel_hi:[1,0]
	v_pk_mul_f32 v[32:33], v[32:33], v[66:67] op_sel_hi:[1,0]
	v_pk_mul_f32 v[30:31], v[30:31], v[66:67] op_sel_hi:[1,0]
	v_pk_mul_f32 v[28:29], v[28:29], v[66:67] op_sel_hi:[1,0]
	v_pk_mul_f32 v[26:27], v[26:27], v[66:67] op_sel_hi:[1,0]
	v_pk_mul_f32 v[24:25], v[24:25], v[66:67] op_sel_hi:[1,0]
	v_pk_mul_f32 v[22:23], v[22:23], v[66:67] op_sel_hi:[1,0]
	v_pk_mul_f32 v[20:21], v[20:21], v[66:67] op_sel_hi:[1,0]
	v_pk_mul_f32 v[18:19], v[18:19], v[66:67] op_sel_hi:[1,0]
	v_pk_mul_f32 v[16:17], v[16:17], v[66:67] op_sel_hi:[1,0]
	v_pk_mul_f32 v[14:15], v[14:15], v[66:67] op_sel_hi:[1,0]
	v_pk_mul_f32 v[12:13], v[12:13], v[66:67] op_sel_hi:[1,0]
	v_pk_mul_f32 v[10:11], v[10:11], v[66:67] op_sel_hi:[1,0]
	v_pk_mul_f32 v[8:9], v[8:9], v[66:67] op_sel_hi:[1,0]
	v_pk_mul_f32 v[6:7], v[6:7], v[66:67] op_sel_hi:[1,0]
	v_pk_mul_f32 v[4:5], v[4:5], v[66:67] op_sel_hi:[1,0]
	v_pk_mul_f32 v[2:3], v[2:3], v[66:67] op_sel_hi:[1,0]
	v_sub_f32_e32 v156, v156, v67
	v_sub_f32_e32 v157, v157, v67
	v_sub_f32_e32 v160, v160, v67
	v_sub_f32_e32 v161, v161, v67
	v_sub_f32_e32 v164, v164, v67
	v_sub_f32_e32 v165, v165, v67
	v_sub_f32_e32 v166, v166, v67
	v_sub_f32_e32 v167, v167, v67
	v_sub_f32_e32 v158, v158, v67
	v_sub_f32_e32 v159, v159, v67
	v_sub_f32_e32 v162, v162, v67
	v_sub_f32_e32 v163, v163, v67
	v_sub_f32_e32 v110, v110, v67
	v_sub_f32_e32 v111, v111, v67
	v_sub_f32_e32 v112, v112, v67
	v_sub_f32_e32 v113, v113, v67
	v_mul_f32_e32 v151, v151, v66
	v_mov_b32_e32 v83, v82
	v_mov_b32_e32 v84, v82
	v_mov_b32_e32 v85, v82
	v_mov_b32_e32 v86, v82
	v_mov_b32_e32 v87, v82
	v_mov_b32_e32 v88, v82
	v_mov_b32_e32 v89, v82
	v_mov_b32_e32 v90, v82
	v_mov_b32_e32 v91, v82
	v_mov_b32_e32 v92, v82
	v_mov_b32_e32 v93, v82
	v_mov_b32_e32 v94, v82
	v_mov_b32_e32 v95, v82
	v_mov_b32_e32 v96, v82
	v_mov_b32_e32 v97, v82
	v_mov_b32_e32 v66, v82
	v_mov_b32_e32 v67, v82
	v_mov_b32_e32 v68, v82
	v_mov_b32_e32 v69, v82
	v_mov_b32_e32 v70, v82
	v_mov_b32_e32 v71, v82
	v_mov_b32_e32 v72, v82
	v_mov_b32_e32 v73, v82
	v_mov_b32_e32 v74, v82
	v_mov_b32_e32 v75, v82
	v_mov_b32_e32 v76, v82
	v_mov_b32_e32 v77, v82
	v_mov_b32_e32 v78, v82
	v_mov_b32_e32 v79, v82
	v_mov_b32_e32 v80, v82
	v_mov_b32_e32 v81, v82
	s_branch .LBB0_581

; template <int DQK, int DV, bool BIAS> ...
;     ...
;         const LAS unsigned char* kb = lds + buf * KBUF + r32 * KP + hi * 16;
; #pragma unroll
;         for (int ks = 0; ks < NKS; ++ks) {
;             const bf16x8 k0 = *(const LAS bf16x8*)(kb + ks * 32), k1 = *(const LAS bf16x8*)(kb + 32 * KP + ks * 32);
;             if (ks == 0) { p0 = __builtin_amdgcn_mfma_f32_32x32x16_bf16(k0, qf[0], negm, 0, 0, 0); p1 = __builtin_amdgcn_mfma_f32_32x32x16_bf16(k1, qf[0], negm, 0, 0, 0); }
;             else { p0 = __builtin_amdgcn_mfma_f32_32x32x16_bf16(k0, qf[ks], p0, 0, 0, 0); p1 = __builtin_amdgcn_mfma_f32_32x32x16_bf16(k1, qf[ks], p1, 0, 0, 0); }
;         }
;         if (BIAS) {
;             asm volatile("s_nop 15\n\ts_nop 7" : "+v"(p0), "+v"(p1));
;             const float d0 = qp - (float)(t * 64 + 4 * hi);
; #pragma unroll
;             for (int r = 0; r < 16; ++r) { const float dk = d0 - (float)((r & 3) + 8 * (r >> 2)); p0[r] = p0[r] - sl2 * fabsf(dk); p1[r] = p1[r] - sl2 * fabsf(dk - 32.f); }
;         } else {
;             asm volatile("s_nop 15\n\ts_nop 7" : "+v"(p0), "+v"(p1));
;         }
;         float mxa = max3f(p0[0], p0[1], p1[0]), mxb = max3f(p0[2], p0[3], p1[1]); mxa = max3f(mxa, p1[2], p1[3]);
; #pragma unroll
;         for (int r = 4; r < 16; r += 4) { mxa = max3f(mxa, p0[r], p0[r + 1]); mxb = max3f(mxb, p0[r + 2], p0[r + 3]); mxa = max3f(mxa, p1[r], p1[r + 1]); mxb = max3f(mxb, p1[r + 2], p1[r + 3]); }
;         float mx = fmaxf(mxa, mxb);
;         if (__any(mx > 8.f)) {
;     ...
;                 for (int j = 0; j < 8; ++j) { e[j] = __builtin_amdgcn_exp2f(hs < 2 ? p0[8 * (hs & 1) + j] : p1[8 * (hs & 1) + j]); ls += e[j]; }
;                 pw[hs].x = cvtpk(e[0], e[1]); pw[hs].y = cvtpk(e[2], e[3]); pw[hs].z = cvtpk(e[4], e[5]); pw[hs].w = cvtpk(e[6], e[7]);
;                 const bf16x8 pbv = __builtin_bit_cast(bf16x8, pw[hs]);
; #pragma unroll
;                 for (int d = 0; d < NDT; ++d) { const LAS unsigned char* vp = vbase + d * 4096 + hs * 1024;
;                     const v4i16_t a0 = __builtin_amdgcn_ds_read_tr16_b64_v4i16((LAS v4i16_t*)vp), a1 = __builtin_amdgcn_ds_read_tr16_b64_v4i16((LAS v4i16_t*)(vp + 512));
;                     const bf16x8 av = {a0[0], a0[1], a0[2], a0[3], a1[0], a1[1], a1[2], a1[3]};
;                     o[d] = __builtin_amdgcn_mfma_f32_32x32x16_bf16(av, pbv, o[d], 0, 0, 0); }
.LBB0_584:
	ds_read_b128 v[192:195], v175 offset:9216
	ds_read_b128 v[196:199], v175 offset:9248
	v_add_f32_e32 v156, 0, v156
	v_add_f32_e32 v156, v157, v156
	v_add_f32_e32 v156, v160, v156
	s_waitcnt lgkmcnt(1)
	v_mfma_f32_32x32x16_bf16 v[98:113], v[192:195], v[114:117], v[82:97]
	ds_read_b128 v[192:195], v175 offset:13824
	ds_read_b128 v[200:203], v175 offset:13856
	v_add_f32_e32 v156, v161, v156
	v_add_f32_e32 v156, v164, v156
	v_add_f32_e32 v150, v150, v156
	v_add_f32_e32 v150, v165, v150
	v_add_f32_e32 v150, v166, v150
	v_add_f32_e32 v150, v167, v150
	s_waitcnt lgkmcnt(1)
	v_mfma_f32_32x32x16_bf16 v[82:97], v[192:195], v[114:117], v[82:97]
	v_add_f32_e32 v150, v177, v150
	v_add_f32_e32 v150, v178, v150
	v_add_f32_e32 v150, v158, v150
	v_add_f32_e32 v150, v159, v150
	ds_read_b128 v[164:167], v175 offset:9280
	v_add_f32_e32 v150, v162, v150
	v_add_f32_e32 v150, v163, v150
	v_mfma_f32_32x32x16_bf16 v[98:113], v[196:199], v[118:121], v[98:113]
	v_add_f32_e32 v150, v179, v150
	v_add_f32_e32 v150, v180, v150
	v_add_f32_e32 v150, v181, v150
	v_add_f32_e32 v150, v152, v150
	ds_read_b128 v[156:159], v175 offset:13888
	ds_read_b128 v[160:163], v175 offset:9312
	v_add_f32_e32 v150, v153, v150
	v_add_f32_e32 v150, v182, v150
	s_waitcnt lgkmcnt(3)
	v_mfma_f32_32x32x16_bf16 v[82:97], v[200:203], v[118:121], v[82:97]
	v_add_f32_e32 v150, v183, v150
	v_add_f32_e32 v150, v154, v150
	v_add_f32_e32 v150, v155, v150
	v_add_f32_e32 v150, v184, v150
	v_add_f32_e32 v150, v185, v150
	v_add_u32_e32 v152, 64, v173
	v_add_f32_e32 v150, v186, v150
	s_waitcnt lgkmcnt(2)
	v_mfma_f32_32x32x16_bf16 v[98:113], v[164:167], v[122:125], v[98:113]
	ds_read_b128 v[164:167], v175 offset:13920
	v_cvt_f32_u32_e32 v152, v152
	v_add_f32_e32 v150, v187, v150
	v_add_f32_e32 v150, v188, v150
	v_add_f32_e32 v150, v191, v150
	v_add_f32_e32 v150, v189, v150
	v_add_f32_e32 v150, v190, v150
	s_waitcnt lgkmcnt(2)
	v_mfma_f32_32x32x16_bf16 v[82:97], v[156:159], v[122:125], v[82:97]
	v_add_f32_e32 v158, v151, v150
	s_waitcnt lgkmcnt(1)
	v_mfma_f32_32x32x16_bf16 v[98:113], v[160:163], v[126:129], v[98:113]
	v_sub_f32_e32 v160, v172, v152
	v_add_f32_e32 v161, -1.0, v160
	v_and_b32_e32 v150, 0x7fffffff, v160
	v_and_b32_e32 v151, 0x7fffffff, v161
	s_waitcnt lgkmcnt(0)
	v_mfma_f32_32x32x16_bf16 v[82:97], v[164:167], v[126:129], v[82:97]
	s_nop 15
	s_nop 7
	s_nop 5
	v_pk_fma_f32 v[150:151], v[142:143], v[150:151], v[98:99] neg_lo:[1,0,0] neg_hi:[1,0,0]
	v_pk_add_f32 v[98:99], v[160:161], s[8:9] op_sel_hi:[1,0]
	s_nop 0
	v_fma_f32 v83, -v143, |v99|, v83
	v_fma_f32 v82, -v142, |v98|, v82
	s_nop 0
	v_pk_add_f32 v[98:99], v[160:161], s[10:11] op_sel_hi:[0,1]
	v_fma_f32 v153, -v143, |v99|, v101
	v_fma_f32 v152, -v142, |v98|, v100
	v_pk_add_f32 v[98:99], v[98:99], s[8:9] op_sel_hi:[1,0]
	v_fma_f32 v99, -v143, |v99|, v85
	v_fma_f32 v98, -v142, |v98|, v84
	v_pk_add_f32 v[84:85], v[160:161], s[22:23] op_sel_hi:[0,1]
	v_fma_f32 v155, -v143, |v85|, v103
	v_fma_f32 v154, -v142, |v84|, v102
	v_pk_add_f32 v[84:85], v[84:85], s[8:9] op_sel_hi:[1,0]
	v_fma_f32 v101, -v143, |v85|, v87
	v_fma_f32 v100, -v142, |v84|, v86
	v_pk_add_f32 v[84:85], v[160:161], s[34:35] op_sel_hi:[0,1]
	v_fma_f32 v157, -v143, |v85|, v105
	v_fma_f32 v156, -v142, |v84|, v104
	v_pk_add_f32 v[84:85], v[84:85], s[8:9] op_sel_hi:[1,0]
	v_fma_f32 v103, -v143, |v85|, v89
	v_fma_f32 v102, -v142, |v84|, v88
	v_pk_add_f32 v[84:85], v[160:161], s[36:37] op_sel_hi:[0,1]
	v_fma_f32 v105, -v143, |v85|, v107
	v_fma_f32 v104, -v142, |v84|, v106
	v_pk_add_f32 v[86:87], v[160:161], s[38:39] op_sel_hi:[0,1]
	v_pk_add_f32 v[84:85], v[84:85], s[8:9] op_sel_hi:[1,0]
	v_fma_f32 v107, -v143, |v87|, v109
	v_fma_f32 v106, -v142, |v86|, v108
	v_fma_f32 v85, -v143, |v85|, v91
	v_fma_f32 v84, -v142, |v84|, v90
	v_pk_add_f32 v[86:87], v[86:87], s[8:9] op_sel_hi:[1,0]
	v_pk_add_f32 v[88:89], v[160:161], s[40:41] op_sel_hi:[0,1]
	v_fma_f32 v87, -v143, |v87|, v93
	v_fma_f32 v86, -v142, |v86|, v92
	v_fma_f32 v93, -v143, |v89|, v111
	v_fma_f32 v92, -v142, |v88|, v110
	v_pk_add_f32 v[88:89], v[88:89], s[8:9] op_sel_hi:[1,0]
	v_fma_f32 v89, -v143, |v89|, v95
	v_fma_f32 v88, -v142, |v88|, v94
	v_pk_add_f32 v[90:91], v[160:161], s[42:43] op_sel_hi:[0,1]
	v_fma_f32 v95, -v143, |v91|, v113
	v_fma_f32 v94, -v142, |v90|, v112
	v_pk_add_f32 v[90:91], v[90:91], s[8:9] op_sel_hi:[1,0]
	v_fma_f32 v91, -v143, |v91|, v97
	v_fma_f32 v90, -v142, |v90|, v96
	v_max3_f32 v96, v150, v151, v82
	v_max3_f32 v97, v152, v153, v83
	s_nop 0
	v_max3_f32 v96, v96, v98, v99
	v_max3_f32 v97, v97, v156, v157
	s_nop 0
	v_max3_f32 v96, v96, v154, v155
	v_max3_f32 v97, v97, v102, v103
	s_nop 0
	v_max3_f32 v96, v96, v100, v101
	v_max3_f32 v97, v97, v106, v107
	s_nop 0
	v_max3_f32 v96, v96, v104, v105
	v_max3_f32 v97, v97, v86, v87
	s_nop 0
	v_max3_f32 v96, v96, v84, v85
	v_max3_f32 v97, v97, v94, v95
	s_nop 0
	v_max3_f32 v96, v96, v92, v93
	v_max3_f32 v97, v97, v90, v91
	s_nop 0
	v_max3_f32 v96, v96, v88, v89
	v_max_f32_e32 v97, v97, v97
	v_max_f32_e32 v96, v96, v96
	v_max_f32_e32 v96, v96, v97
	v_cmp_lt_f32_e32 vcc, s52, v96
	s_cbranch_vccz .LBB0_575
; template <int DQK, int DV, bool BIAS> ...
;     ...
;         if (__any(mx > 8.f)) {
;             mx = fmaxf(mx, __shfl_xor(mx, 32));
;             const float dl = fmaxf(mx, 0.f); mhat += dl;
;             const float f = __builtin_amdgcn_exp2f(-dl);
; #pragma unroll
;             for (int r = 0; r < 16; ++r) { p0[r] -= dl; p1[r] -= dl; negm[r] = -mhat; }
;             l *= f;
; #pragma unroll
;             for (int d = 0; d < NDT; ++d)
; #pragma unroll
;                 for (int r = 0; r < 16; ++r) o[d][r] *= f;
;         }
	v_and_b32_e32 v67, 64, v170
	v_xor_b32_e32 v66, 32, v170
	v_add_u32_e32 v67, 64, v67
	v_cmp_lt_i32_e32 vcc, v66, v67
	s_nop 1
	v_cndmask_b32_e32 v66, v170, v66, vcc
	v_lshlrev_b32_e32 v66, 2, v66
	ds_bpermute_b32 v66, v66, v96
	s_waitcnt lgkmcnt(0)
	v_max3_f32 v67, v96, v66, 0
	v_exp_f32_e64 v68, -v67
	v_add_f32_e32 v176, v176, v67
	v_xor_b32_e32 v66, 0x80000000, v176
	v_sub_f32_e32 v82, v82, v67
	v_sub_f32_e32 v83, v83, v67
	v_sub_f32_e32 v98, v98, v67
	v_sub_f32_e32 v99, v99, v67
	v_sub_f32_e32 v100, v100, v67
	v_sub_f32_e32 v101, v101, v67
	v_sub_f32_e32 v102, v102, v67
	v_sub_f32_e32 v103, v103, v67
	v_sub_f32_e32 v84, v84, v67
	v_sub_f32_e32 v85, v85, v67
	v_sub_f32_e32 v86, v86, v67
	v_sub_f32_e32 v87, v87, v67
	v_sub_f32_e32 v88, v88, v67
	v_sub_f32_e32 v89, v89, v67
	v_sub_f32_e32 v90, v90, v67
	v_sub_f32_e32 v91, v91, v67
	v_pk_mul_f32 v[64:65], v[64:65], v[68:69] op_sel_hi:[1,0]
	v_pk_mul_f32 v[62:63], v[62:63], v[68:69] op_sel_hi:[1,0]
	v_pk_mul_f32 v[60:61], v[60:61], v[68:69] op_sel_hi:[1,0]
	v_pk_mul_f32 v[58:59], v[58:59], v[68:69] op_sel_hi:[1,0]
	v_pk_mul_f32 v[56:57], v[56:57], v[68:69] op_sel_hi:[1,0]
	v_pk_mul_f32 v[54:55], v[54:55], v[68:69] op_sel_hi:[1,0]
	v_pk_mul_f32 v[52:53], v[52:53], v[68:69] op_sel_hi:[1,0]
	v_pk_mul_f32 v[50:51], v[50:51], v[68:69] op_sel_hi:[1,0]
	v_pk_mul_f32 v[48:49], v[48:49], v[68:69] op_sel_hi:[1,0]
	v_pk_mul_f32 v[46:47], v[46:47], v[68:69] op_sel_hi:[1,0]
	v_pk_mul_f32 v[44:45], v[44:45], v[68:69] op_sel_hi:[1,0]
	v_pk_mul_f32 v[42:43], v[42:43], v[68:69] op_sel_hi:[1,0]
	v_pk_mul_f32 v[40:41], v[40:41], v[68:69] op_sel_hi:[1,0]
	v_pk_mul_f32 v[38:39], v[38:39], v[68:69] op_sel_hi:[1,0]
	v_pk_mul_f32 v[36:37], v[36:37], v[68:69] op_sel_hi:[1,0]
	v_pk_mul_f32 v[34:35], v[34:35], v[68:69] op_sel_hi:[1,0]
	v_pk_mul_f32 v[32:33], v[32:33], v[68:69] op_sel_hi:[1,0]
	v_pk_mul_f32 v[30:31], v[30:31], v[68:69] op_sel_hi:[1,0]
	v_pk_mul_f32 v[28:29], v[28:29], v[68:69] op_sel_hi:[1,0]
	v_pk_mul_f32 v[26:27], v[26:27], v[68:69] op_sel_hi:[1,0]
	v_pk_mul_f32 v[24:25], v[24:25], v[68:69] op_sel_hi:[1,0]
	v_pk_mul_f32 v[22:23], v[22:23], v[68:69] op_sel_hi:[1,0]
	v_pk_mul_f32 v[20:21], v[20:21], v[68:69] op_sel_hi:[1,0]
	v_pk_mul_f32 v[18:19], v[18:19], v[68:69] op_sel_hi:[1,0]
	v_pk_mul_f32 v[16:17], v[16:17], v[68:69] op_sel_hi:[1,0]
	v_pk_mul_f32 v[14:15], v[14:15], v[68:69] op_sel_hi:[1,0]
	v_pk_mul_f32 v[12:13], v[12:13], v[68:69] op_sel_hi:[1,0]
	v_pk_mul_f32 v[10:11], v[10:11], v[68:69] op_sel_hi:[1,0]
	v_pk_mul_f32 v[8:9], v[8:9], v[68:69] op_sel_hi:[1,0]
	v_pk_mul_f32 v[6:7], v[6:7], v[68:69] op_sel_hi:[1,0]
	v_pk_mul_f32 v[4:5], v[4:5], v[68:69] op_sel_hi:[1,0]
	v_pk_mul_f32 v[2:3], v[2:3], v[68:69] op_sel_hi:[1,0]
	v_sub_f32_e32 v150, v150, v67
	v_sub_f32_e32 v151, v151, v67
	v_sub_f32_e32 v152, v152, v67
	v_sub_f32_e32 v153, v153, v67
	v_sub_f32_e32 v154, v154, v67
	v_sub_f32_e32 v155, v155, v67
	v_sub_f32_e32 v156, v156, v67
	v_sub_f32_e32 v157, v157, v67
	v_sub_f32_e32 v104, v104, v67
	v_sub_f32_e32 v105, v105, v67
	v_sub_f32_e32 v106, v106, v67
	v_sub_f32_e32 v107, v107, v67
	v_sub_f32_e32 v92, v92, v67
	v_sub_f32_e32 v93, v93, v67
	v_sub_f32_e32 v94, v94, v67
	v_sub_f32_e32 v95, v95, v67
	v_mul_f32_e32 v158, v158, v68
	v_mov_b32_e32 v67, v66
	v_mov_b32_e32 v68, v66
	v_mov_b32_e32 v69, v66
	v_mov_b32_e32 v70, v66
	v_mov_b32_e32 v71, v66
	v_mov_b32_e32 v72, v66
	v_mov_b32_e32 v73, v66
	v_mov_b32_e32 v74, v66
	v_mov_b32_e32 v75, v66
	v_mov_b32_e32 v76, v66
	v_mov_b32_e32 v77, v66
	v_mov_b32_e32 v78, v66
	v_mov_b32_e32 v79, v66
	v_mov_b32_e32 v80, v66
	v_mov_b32_e32 v81, v66
	s_branch .LBB0_575

; #define LAS __attribute__((address_space(3)))
; __device__ __forceinline__ float max3f(float a, float b, float c) { float r; asm("v_max3_f32 %0, %1, %2, %3" : "=v"(r) : "v"(a), "v"(b), "v"(c)); return r; }
; template <int DQK, int DV, bool BIAS> ...
;     ...
;         const LAS unsigned char* kb = lds + buf * KBUF + r32 * KP + hi * 16;
; #pragma unroll
;         for (int ks = 0; ks < NKS; ++ks) {
;             const bf16x8 k0 = *(const LAS bf16x8*)(kb + ks * 32), k1 = *(const LAS bf16x8*)(kb + 32 * KP + ks * 32);
;             if (ks == 0) { p0 = __builtin_amdgcn_mfma_f32_32x32x16_bf16(k0, qf[0], negm, 0, 0, 0); p1 = __builtin_amdgcn_mfma_f32_32x32x16_bf16(k1, qf[0], negm, 0, 0, 0); }
;             else { p0 = __builtin_amdgcn_mfma_f32_32x32x16_bf16(k0, qf[ks], p0, 0, 0, 0); p1 = __builtin_amdgcn_mfma_f32_32x32x16_bf16(k1, qf[ks], p1, 0, 0, 0); }
;         }
;         if (BIAS) {
;             asm volatile("s_nop 15\n\ts_nop 7" : "+v"(p0), "+v"(p1));
;             const float d0 = qp - (float)(t * 64 + 4 * hi);
; #pragma unroll
;             for (int r = 0; r < 16; ++r) { const float dk = d0 - (float)((r & 3) + 8 * (r >> 2)); p0[r] = p0[r] - sl2 * fabsf(dk); p1[r] = p1[r] - sl2 * fabsf(dk - 32.f); }
;         } else {
;             asm volatile("s_nop 15\n\ts_nop 7" : "+v"(p0), "+v"(p1));
;         }
;         float mxa = max3f(p0[0], p0[1], p1[0]), mxb = max3f(p0[2], p0[3], p1[1]); mxa = max3f(mxa, p1[2], p1[3]);
; #pragma unroll
;         for (int r = 4; r < 16; r += 4) { mxa = max3f(mxa, p0[r], p0[r + 1]); mxb = max3f(mxb, p0[r + 2], p0[r + 3]); mxa = max3f(mxa, p1[r], p1[r + 1]); mxb = max3f(mxb, p1[r + 2], p1[r + 3]); }
;         float mx = fmaxf(mxa, mxb);
;         if (__any(mx > 8.f)) {
.LBB0_590:
	ds_read_b128 v[82:85], v179
	ds_read_b128 v[152:155], v179 offset:32
	ds_read_b128 v[156:159], v179 offset:4608
	ds_read_b128 v[160:163], v179 offset:4640
	v_cvt_f32_u32_e32 v150, v177
	s_waitcnt lgkmcnt(3)
	v_mfma_f32_32x32x16_bf16 v[98:113], v[82:85], v[114:117], v[66:81]
	v_sub_f32_e32 v182, v176, v150
	v_add_f32_e32 v183, -1.0, v182
	s_waitcnt lgkmcnt(1)
	v_mfma_f32_32x32x16_bf16 v[82:97], v[156:159], v[114:117], v[66:81]
	v_mfma_f32_32x32x16_bf16 v[98:113], v[152:155], v[118:121], v[98:113]
	ds_read_b128 v[152:155], v179 offset:64
	ds_read_b128 v[156:159], v179 offset:96
	s_waitcnt lgkmcnt(2)
	v_mfma_f32_32x32x16_bf16 v[82:97], v[160:163], v[118:121], v[82:97]
	s_waitcnt lgkmcnt(1)
	v_mfma_f32_32x32x16_bf16 v[98:113], v[152:155], v[122:125], v[98:113]
	ds_read_b128 v[152:155], v179 offset:4672
	ds_read_b128 v[160:163], v179 offset:4704
	s_waitcnt lgkmcnt(1)
	v_mfma_f32_32x32x16_bf16 v[82:97], v[152:155], v[122:125], v[82:97]
	v_and_b32_e32 v152, 0x7fffffff, v182
	v_and_b32_e32 v153, 0x7fffffff, v183
	v_mfma_f32_32x32x16_bf16 v[98:113], v[156:159], v[126:129], v[98:113]
	s_waitcnt lgkmcnt(0)
	v_mfma_f32_32x32x16_bf16 v[82:97], v[160:163], v[126:129], v[82:97]
	s_nop 15
	s_nop 7
	s_nop 9
	v_pk_fma_f32 v[156:157], v[142:143], v[152:153], v[98:99] neg_lo:[1,0,0] neg_hi:[1,0,0]
	v_pk_add_f32 v[98:99], v[182:183], s[6:7] op_sel_hi:[1,0]
	s_nop 0
	v_fma_f32 v99, -v143, |v99|, v83
	v_fma_f32 v98, -v142, |v98|, v82
	v_pk_add_f32 v[82:83], v[182:183], s[8:9] op_sel_hi:[0,1]
	v_fma_f32 v161, -v143, |v83|, v101
	v_fma_f32 v160, -v142, |v82|, v100
	v_pk_add_f32 v[82:83], v[82:83], s[6:7] op_sel_hi:[1,0]
	v_fma_f32 v153, -v143, |v83|, v85
	v_fma_f32 v152, -v142, |v82|, v84
	v_pk_add_f32 v[82:83], v[182:183], s[10:11] op_sel_hi:[0,1]
	v_fma_f32 v165, -v143, |v83|, v103
	v_fma_f32 v164, -v142, |v82|, v102
	v_pk_add_f32 v[82:83], v[82:83], s[6:7] op_sel_hi:[1,0]
	v_fma_f32 v103, -v143, |v83|, v87
	v_fma_f32 v102, -v142, |v82|, v86
	v_pk_add_f32 v[82:83], v[182:183], s[22:23] op_sel_hi:[0,1]
	v_fma_f32 v167, -v143, |v83|, v105
	v_fma_f32 v166, -v142, |v82|, v104
	v_pk_add_f32 v[82:83], v[82:83], s[6:7] op_sel_hi:[1,0]
	v_fma_f32 v155, -v143, |v83|, v89
	v_fma_f32 v154, -v142, |v82|, v88
	v_pk_add_f32 v[82:83], v[182:183], s[34:35] op_sel_hi:[0,1]
	v_fma_f32 v159, -v143, |v83|, v107
	v_fma_f32 v158, -v142, |v82|, v106
	v_pk_add_f32 v[82:83], v[82:83], s[6:7] op_sel_hi:[1,0]
	v_fma_f32 v101, -v143, |v83|, v91
	v_fma_f32 v100, -v142, |v82|, v90
	v_pk_add_f32 v[82:83], v[182:183], s[36:37] op_sel_hi:[0,1]
	v_fma_f32 v163, -v143, |v83|, v109
	v_fma_f32 v162, -v142, |v82|, v108
	v_pk_add_f32 v[82:83], v[82:83], s[6:7] op_sel_hi:[1,0]
	v_fma_f32 v105, -v143, |v83|, v93
	v_fma_f32 v104, -v142, |v82|, v92
	v_pk_add_f32 v[82:83], v[182:183], s[38:39] op_sel_hi:[0,1]
	v_fma_f32 v111, -v143, |v83|, v111
	v_fma_f32 v110, -v142, |v82|, v110
	v_pk_add_f32 v[82:83], v[82:83], s[6:7] op_sel_hi:[1,0]
	v_fma_f32 v107, -v143, |v83|, v95
	v_fma_f32 v106, -v142, |v82|, v94
	v_pk_add_f32 v[82:83], v[182:183], s[40:41] op_sel_hi:[0,1]
	v_fma_f32 v113, -v143, |v83|, v113
	v_fma_f32 v112, -v142, |v82|, v112
	v_pk_add_f32 v[82:83], v[82:83], s[6:7] op_sel_hi:[1,0]
	v_fma_f32 v109, -v143, |v83|, v97
	v_fma_f32 v108, -v142, |v82|, v96
	v_max3_f32 v82, v156, v157, v98
	v_max3_f32 v83, v160, v161, v99
	s_nop 0
	v_max3_f32 v82, v82, v152, v153
	v_max3_f32 v83, v83, v166, v167
	s_nop 0
	v_max3_f32 v82, v82, v164, v165
	v_max3_f32 v83, v83, v154, v155
	s_nop 0
	v_max3_f32 v82, v82, v102, v103
	v_max3_f32 v83, v83, v162, v163
	s_nop 0
	v_max3_f32 v82, v82, v158, v159
	v_max3_f32 v83, v83, v104, v105
	s_nop 0
	v_max3_f32 v82, v82, v100, v101
	v_max3_f32 v83, v83, v112, v113
	s_nop 0
	v_max3_f32 v82, v82, v110, v111
	v_max3_f32 v83, v83, v108, v109
	s_nop 0
	v_max3_f32 v82, v82, v106, v107
	v_max_f32_e32 v83, v83, v83
	v_max_f32_e32 v82, v82, v82
	v_max_f32_e32 v82, v82, v83
	v_cmp_lt_f32_e32 vcc, s44, v82
	s_cbranch_vccz .LBB0_592
; template <int DQK, int DV, bool BIAS> ...
;     ...
;         if (__any(mx > 8.f)) {
;             mx = fmaxf(mx, __shfl_xor(mx, 32));
;             const float dl = fmaxf(mx, 0.f); mhat += dl;
;             const float f = __builtin_amdgcn_exp2f(-dl);
; #pragma unroll
;             for (int r = 0; r < 16; ++r) { p0[r] -= dl; p1[r] -= dl; negm[r] = -mhat; }
;             l *= f;
; #pragma unroll
;             for (int d = 0; d < NDT; ++d)
; #pragma unroll
;                 for (int r = 0; r < 16; ++r) o[d][r] *= f;
;         }
	ds_bpermute_b32 v66, v168, v82
	s_waitcnt lgkmcnt(0)
	v_max3_f32 v67, v82, v66, 0
	v_exp_f32_e64 v66, -v67
	v_add_f32_e32 v180, v180, v67
	v_xor_b32_e32 v82, 0x80000000, v180
	v_sub_f32_e32 v98, v98, v67
	v_sub_f32_e32 v99, v99, v67
	v_sub_f32_e32 v152, v152, v67
	v_sub_f32_e32 v153, v153, v67
	v_sub_f32_e32 v102, v102, v67
	v_sub_f32_e32 v103, v103, v67
	v_sub_f32_e32 v154, v154, v67
	v_sub_f32_e32 v155, v155, v67
	v_sub_f32_e32 v100, v100, v67
	v_sub_f32_e32 v101, v101, v67
	v_sub_f32_e32 v104, v104, v67
	v_sub_f32_e32 v105, v105, v67
	v_sub_f32_e32 v106, v106, v67
	v_sub_f32_e32 v107, v107, v67
	v_sub_f32_e32 v108, v108, v67
	v_sub_f32_e32 v109, v109, v67
	v_pk_mul_f32 v[16:17], v[16:17], v[66:67] op_sel_hi:[1,0]
	v_pk_mul_f32 v[14:15], v[14:15], v[66:67] op_sel_hi:[1,0]
	v_pk_mul_f32 v[12:13], v[12:13], v[66:67] op_sel_hi:[1,0]
	v_pk_mul_f32 v[10:11], v[10:11], v[66:67] op_sel_hi:[1,0]
	v_pk_mul_f32 v[8:9], v[8:9], v[66:67] op_sel_hi:[1,0]
	v_pk_mul_f32 v[6:7], v[6:7], v[66:67] op_sel_hi:[1,0]
	v_pk_mul_f32 v[4:5], v[4:5], v[66:67] op_sel_hi:[1,0]
	v_pk_mul_f32 v[2:3], v[2:3], v[66:67] op_sel_hi:[1,0]
	v_pk_mul_f32 v[32:33], v[32:33], v[66:67] op_sel_hi:[1,0]
	v_pk_mul_f32 v[30:31], v[30:31], v[66:67] op_sel_hi:[1,0]
	v_pk_mul_f32 v[28:29], v[28:29], v[66:67] op_sel_hi:[1,0]
	v_pk_mul_f32 v[26:27], v[26:27], v[66:67] op_sel_hi:[1,0]
	v_pk_mul_f32 v[24:25], v[24:25], v[66:67] op_sel_hi:[1,0]
	v_pk_mul_f32 v[22:23], v[22:23], v[66:67] op_sel_hi:[1,0]
	v_pk_mul_f32 v[20:21], v[20:21], v[66:67] op_sel_hi:[1,0]
	v_pk_mul_f32 v[18:19], v[18:19], v[66:67] op_sel_hi:[1,0]
	v_pk_mul_f32 v[48:49], v[48:49], v[66:67] op_sel_hi:[1,0]
	v_pk_mul_f32 v[46:47], v[46:47], v[66:67] op_sel_hi:[1,0]
	v_pk_mul_f32 v[44:45], v[44:45], v[66:67] op_sel_hi:[1,0]
	v_pk_mul_f32 v[42:43], v[42:43], v[66:67] op_sel_hi:[1,0]
	v_pk_mul_f32 v[40:41], v[40:41], v[66:67] op_sel_hi:[1,0]
	v_pk_mul_f32 v[38:39], v[38:39], v[66:67] op_sel_hi:[1,0]
	v_pk_mul_f32 v[36:37], v[36:37], v[66:67] op_sel_hi:[1,0]
	v_pk_mul_f32 v[34:35], v[34:35], v[66:67] op_sel_hi:[1,0]
	v_pk_mul_f32 v[64:65], v[64:65], v[66:67] op_sel_hi:[1,0]
	v_pk_mul_f32 v[62:63], v[62:63], v[66:67] op_sel_hi:[1,0]
	v_pk_mul_f32 v[60:61], v[60:61], v[66:67] op_sel_hi:[1,0]
	v_pk_mul_f32 v[58:59], v[58:59], v[66:67] op_sel_hi:[1,0]
	v_pk_mul_f32 v[56:57], v[56:57], v[66:67] op_sel_hi:[1,0]
	v_pk_mul_f32 v[54:55], v[54:55], v[66:67] op_sel_hi:[1,0]
	v_pk_mul_f32 v[52:53], v[52:53], v[66:67] op_sel_hi:[1,0]
	v_pk_mul_f32 v[50:51], v[50:51], v[66:67] op_sel_hi:[1,0]
	v_sub_f32_e32 v156, v156, v67
	v_sub_f32_e32 v157, v157, v67
	v_sub_f32_e32 v160, v160, v67
	v_sub_f32_e32 v161, v161, v67
	v_sub_f32_e32 v164, v164, v67
	v_sub_f32_e32 v165, v165, v67
	v_sub_f32_e32 v166, v166, v67
	v_sub_f32_e32 v167, v167, v67
	v_sub_f32_e32 v158, v158, v67
	v_sub_f32_e32 v159, v159, v67
	v_sub_f32_e32 v162, v162, v67
	v_sub_f32_e32 v163, v163, v67
	v_sub_f32_e32 v110, v110, v67
	v_sub_f32_e32 v111, v111, v67
	v_sub_f32_e32 v112, v112, v67
	v_sub_f32_e32 v113, v113, v67
	v_mul_f32_e32 v151, v151, v66
	v_mov_b32_e32 v83, v82
	v_mov_b32_e32 v84, v82
	v_mov_b32_e32 v85, v82
	v_mov_b32_e32 v86, v82
	v_mov_b32_e32 v87, v82
	v_mov_b32_e32 v88, v82
	v_mov_b32_e32 v89, v82
	v_mov_b32_e32 v90, v82
	v_mov_b32_e32 v91, v82
	v_mov_b32_e32 v92, v82
	v_mov_b32_e32 v93, v82
	v_mov_b32_e32 v94, v82
	v_mov_b32_e32 v95, v82
	v_mov_b32_e32 v96, v82
	v_mov_b32_e32 v97, v82
	v_mov_b32_e32 v66, v82
	v_mov_b32_e32 v67, v82
	v_mov_b32_e32 v68, v82
	v_mov_b32_e32 v69, v82
	v_mov_b32_e32 v70, v82
	v_mov_b32_e32 v71, v82
	v_mov_b32_e32 v72, v82
	v_mov_b32_e32 v73, v82
	v_mov_b32_e32 v74, v82
	v_mov_b32_e32 v75, v82
	v_mov_b32_e32 v76, v82
	v_mov_b32_e32 v77, v82
	v_mov_b32_e32 v78, v82
	v_mov_b32_e32 v79, v82
	v_mov_b32_e32 v80, v82
	v_mov_b32_e32 v81, v82
	s_branch .LBB0_593

; #define LAS __attribute__((address_space(3)))
; __device__ __forceinline__ float max3f(float a, float b, float c) { float r; asm("v_max3_f32 %0, %1, %2, %3" : "=v"(r) : "v"(a), "v"(b), "v"(c)); return r; }
; template <int DQK, int DV, bool BIAS> ...
;     ...
;         const LAS unsigned char* kb = lds + buf * KBUF + r32 * KP + hi * 16;
; #pragma unroll
;         for (int ks = 0; ks < NKS; ++ks) {
;             const bf16x8 k0 = *(const LAS bf16x8*)(kb + ks * 32), k1 = *(const LAS bf16x8*)(kb + 32 * KP + ks * 32);
;             if (ks == 0) { p0 = __builtin_amdgcn_mfma_f32_32x32x16_bf16(k0, qf[0], negm, 0, 0, 0); p1 = __builtin_amdgcn_mfma_f32_32x32x16_bf16(k1, qf[0], negm, 0, 0, 0); }
;             else { p0 = __builtin_amdgcn_mfma_f32_32x32x16_bf16(k0, qf[ks], p0, 0, 0, 0); p1 = __builtin_amdgcn_mfma_f32_32x32x16_bf16(k1, qf[ks], p1, 0, 0, 0); }
;         }
;         if (BIAS) {
;             asm volatile("s_nop 15\n\ts_nop 7" : "+v"(p0), "+v"(p1));
;             const float d0 = qp - (float)(t * 64 + 4 * hi);
; #pragma unroll
;             for (int r = 0; r < 16; ++r) { const float dk = d0 - (float)((r & 3) + 8 * (r >> 2)); p0[r] = p0[r] - sl2 * fabsf(dk); p1[r] = p1[r] - sl2 * fabsf(dk - 32.f); }
;         } else {
;             asm volatile("s_nop 15\n\ts_nop 7" : "+v"(p0), "+v"(p1));
;         }
;         float mxa = max3f(p0[0], p0[1], p1[0]), mxb = max3f(p0[2], p0[3], p1[1]); mxa = max3f(mxa, p1[2], p1[3]);
; #pragma unroll
;         for (int r = 4; r < 16; r += 4) { mxa = max3f(mxa, p0[r], p0[r + 1]); mxb = max3f(mxb, p0[r + 2], p0[r + 3]); mxa = max3f(mxa, p1[r], p1[r + 1]); mxb = max3f(mxb, p1[r + 2], p1[r + 3]); }
;         float mx = fmaxf(mxa, mxb);
;         if (__any(mx > 8.f)) {
.LBB0_596:
	ds_read_b128 v[196:199], v179 offset:9216
	ds_read_b128 v[200:203], v179 offset:9248
	v_add_f32_e32 v156, 0, v156
	v_add_f32_e32 v156, v157, v156
	v_add_f32_e32 v156, v160, v156
	s_waitcnt lgkmcnt(1)
	v_mfma_f32_32x32x16_bf16 v[98:113], v[196:199], v[114:117], v[82:97]
	ds_read_b128 v[196:199], v179 offset:13824
	ds_read_b128 v[204:207], v179 offset:13856
	v_add_f32_e32 v156, v161, v156
	v_add_f32_e32 v156, v164, v156
	v_add_f32_e32 v150, v150, v156
	v_add_f32_e32 v150, v165, v150
	v_add_f32_e32 v150, v166, v150
	v_add_f32_e32 v150, v167, v150
	s_waitcnt lgkmcnt(1)
	v_mfma_f32_32x32x16_bf16 v[82:97], v[196:199], v[114:117], v[82:97]
	v_add_f32_e32 v150, v181, v150
	v_add_f32_e32 v150, v182, v150
	v_add_f32_e32 v150, v158, v150
	v_add_f32_e32 v150, v159, v150
	ds_read_b128 v[164:167], v179 offset:9280
	v_add_f32_e32 v150, v162, v150
	v_add_f32_e32 v150, v163, v150
	v_mfma_f32_32x32x16_bf16 v[98:113], v[200:203], v[118:121], v[98:113]
	v_add_f32_e32 v150, v183, v150
	v_add_f32_e32 v150, v184, v150
	v_add_f32_e32 v150, v185, v150
	v_add_f32_e32 v150, v152, v150
	ds_read_b128 v[156:159], v179 offset:13888
	ds_read_b128 v[160:163], v179 offset:9312
	v_add_f32_e32 v150, v153, v150
	v_add_f32_e32 v150, v186, v150
	s_waitcnt lgkmcnt(3)
	v_mfma_f32_32x32x16_bf16 v[82:97], v[204:207], v[118:121], v[82:97]
	v_add_f32_e32 v150, v187, v150
	v_add_f32_e32 v150, v154, v150
	v_add_f32_e32 v150, v155, v150
	v_add_f32_e32 v150, v188, v150
	v_add_f32_e32 v150, v189, v150
	v_add_u32_e32 v152, 64, v177
	v_add_f32_e32 v150, v190, v150
	s_waitcnt lgkmcnt(2)
	v_mfma_f32_32x32x16_bf16 v[98:113], v[164:167], v[122:125], v[98:113]
	ds_read_b128 v[164:167], v179 offset:13920
	v_cvt_f32_u32_e32 v152, v152
	v_add_f32_e32 v150, v191, v150
	v_add_f32_e32 v150, v192, v150
	v_add_f32_e32 v150, v195, v150
	v_add_f32_e32 v150, v193, v150
	v_add_f32_e32 v150, v194, v150
	s_waitcnt lgkmcnt(2)
	v_mfma_f32_32x32x16_bf16 v[82:97], v[156:159], v[122:125], v[82:97]
	v_add_f32_e32 v158, v151, v150
	s_waitcnt lgkmcnt(1)
	v_mfma_f32_32x32x16_bf16 v[98:113], v[160:163], v[126:129], v[98:113]
	v_sub_f32_e32 v160, v176, v152
	v_add_f32_e32 v161, -1.0, v160
	v_and_b32_e32 v150, 0x7fffffff, v160
	v_and_b32_e32 v151, 0x7fffffff, v161
	s_waitcnt lgkmcnt(0)
	v_mfma_f32_32x32x16_bf16 v[82:97], v[164:167], v[126:129], v[82:97]
	s_nop 15
	s_nop 7
	s_nop 5
	v_pk_fma_f32 v[150:151], v[142:143], v[150:151], v[98:99] neg_lo:[1,0,0] neg_hi:[1,0,0]
	v_pk_add_f32 v[98:99], v[160:161], s[6:7] op_sel_hi:[1,0]
	s_nop 0
	v_fma_f32 v83, -v143, |v99|, v83
	v_fma_f32 v82, -v142, |v98|, v82
	s_nop 0
	v_pk_add_f32 v[98:99], v[160:161], s[8:9] op_sel_hi:[0,1]
	v_fma_f32 v153, -v143, |v99|, v101
	v_fma_f32 v152, -v142, |v98|, v100
	v_pk_add_f32 v[98:99], v[98:99], s[6:7] op_sel_hi:[1,0]
	v_fma_f32 v99, -v143, |v99|, v85
	v_fma_f32 v98, -v142, |v98|, v84
	v_pk_add_f32 v[84:85], v[160:161], s[10:11] op_sel_hi:[0,1]
	v_fma_f32 v155, -v143, |v85|, v103
	v_fma_f32 v154, -v142, |v84|, v102
	v_pk_add_f32 v[84:85], v[84:85], s[6:7] op_sel_hi:[1,0]
	v_fma_f32 v101, -v143, |v85|, v87
	v_fma_f32 v100, -v142, |v84|, v86
	v_pk_add_f32 v[84:85], v[160:161], s[22:23] op_sel_hi:[0,1]
	v_fma_f32 v157, -v143, |v85|, v105
	v_fma_f32 v156, -v142, |v84|, v104
	v_pk_add_f32 v[84:85], v[84:85], s[6:7] op_sel_hi:[1,0]
	v_fma_f32 v103, -v143, |v85|, v89
	v_fma_f32 v102, -v142, |v84|, v88
	v_pk_add_f32 v[84:85], v[160:161], s[34:35] op_sel_hi:[0,1]
	v_fma_f32 v105, -v143, |v85|, v107
	v_fma_f32 v104, -v142, |v84|, v106
	v_pk_add_f32 v[86:87], v[160:161], s[36:37] op_sel_hi:[0,1]
	v_pk_add_f32 v[84:85], v[84:85], s[6:7] op_sel_hi:[1,0]
	v_fma_f32 v107, -v143, |v87|, v109
	v_fma_f32 v106, -v142, |v86|, v108
	v_fma_f32 v85, -v143, |v85|, v91
	v_fma_f32 v84, -v142, |v84|, v90
	v_pk_add_f32 v[86:87], v[86:87], s[6:7] op_sel_hi:[1,0]
	v_pk_add_f32 v[88:89], v[160:161], s[38:39] op_sel_hi:[0,1]
	v_fma_f32 v87, -v143, |v87|, v93
	v_fma_f32 v86, -v142, |v86|, v92
	v_fma_f32 v93, -v143, |v89|, v111
	v_fma_f32 v92, -v142, |v88|, v110
	v_pk_add_f32 v[88:89], v[88:89], s[6:7] op_sel_hi:[1,0]
	v_fma_f32 v89, -v143, |v89|, v95
	v_fma_f32 v88, -v142, |v88|, v94
	v_pk_add_f32 v[90:91], v[160:161], s[40:41] op_sel_hi:[0,1]
	v_fma_f32 v95, -v143, |v91|, v113
	v_fma_f32 v94, -v142, |v90|, v112
	v_pk_add_f32 v[90:91], v[90:91], s[6:7] op_sel_hi:[1,0]
	v_fma_f32 v91, -v143, |v91|, v97
	v_fma_f32 v90, -v142, |v90|, v96
	v_max3_f32 v96, v150, v151, v82
	v_max3_f32 v97, v152, v153, v83
	s_nop 0
	v_max3_f32 v96, v96, v98, v99
	v_max3_f32 v97, v97, v156, v157
	s_nop 0
	v_max3_f32 v96, v96, v154, v155
	v_max3_f32 v97, v97, v102, v103
	s_nop 0
	v_max3_f32 v96, v96, v100, v101
	v_max3_f32 v97, v97, v106, v107
	s_nop 0
	v_max3_f32 v96, v96, v104, v105
	v_max3_f32 v97, v97, v86, v87
	s_nop 0
	v_max3_f32 v96, v96, v84, v85
	v_max3_f32 v97, v97, v94, v95
	s_nop 0
	v_max3_f32 v96, v96, v92, v93
	v_max3_f32 v97, v97, v90, v91
	s_nop 0
	v_max3_f32 v96, v96, v88, v89
	v_max_f32_e32 v97, v97, v97
	v_max_f32_e32 v96, v96, v96
	v_max_f32_e32 v96, v96, v97
	v_cmp_lt_f32_e32 vcc, s44, v96
	s_cbranch_vccz .LBB0_587
; template <int DQK, int DV, bool BIAS> ...
;     ...
;         if (__any(mx > 8.f)) {
;             mx = fmaxf(mx, __shfl_xor(mx, 32));
;             const float dl = fmaxf(mx, 0.f); mhat += dl;
;             const float f = __builtin_amdgcn_exp2f(-dl);
; #pragma unroll
;             for (int r = 0; r < 16; ++r) { p0[r] -= dl; p1[r] -= dl; negm[r] = -mhat; }
;             l *= f;
; #pragma unroll
;             for (int d = 0; d < NDT; ++d)
; #pragma unroll
;                 for (int r = 0; r < 16; ++r) o[d][r] *= f;
;         }
	ds_bpermute_b32 v66, v168, v96
	s_waitcnt lgkmcnt(0)
	v_max3_f32 v67, v96, v66, 0
	v_exp_f32_e64 v68, -v67
	v_add_f32_e32 v180, v180, v67
	v_xor_b32_e32 v66, 0x80000000, v180
	v_sub_f32_e32 v82, v82, v67
	v_sub_f32_e32 v83, v83, v67
	v_sub_f32_e32 v98, v98, v67
	v_sub_f32_e32 v99, v99, v67
	v_sub_f32_e32 v100, v100, v67
	v_sub_f32_e32 v101, v101, v67
	v_sub_f32_e32 v102, v102, v67
	v_sub_f32_e32 v103, v103, v67
	v_sub_f32_e32 v84, v84, v67
	v_sub_f32_e32 v85, v85, v67
	v_sub_f32_e32 v86, v86, v67
	v_sub_f32_e32 v87, v87, v67
	v_sub_f32_e32 v88, v88, v67
	v_sub_f32_e32 v89, v89, v67
	v_sub_f32_e32 v90, v90, v67
	v_sub_f32_e32 v91, v91, v67
	v_pk_mul_f32 v[16:17], v[16:17], v[68:69] op_sel_hi:[1,0]
	v_pk_mul_f32 v[14:15], v[14:15], v[68:69] op_sel_hi:[1,0]
	v_pk_mul_f32 v[12:13], v[12:13], v[68:69] op_sel_hi:[1,0]
	v_pk_mul_f32 v[10:11], v[10:11], v[68:69] op_sel_hi:[1,0]
	v_pk_mul_f32 v[8:9], v[8:9], v[68:69] op_sel_hi:[1,0]
	v_pk_mul_f32 v[6:7], v[6:7], v[68:69] op_sel_hi:[1,0]
	v_pk_mul_f32 v[4:5], v[4:5], v[68:69] op_sel_hi:[1,0]
	v_pk_mul_f32 v[2:3], v[2:3], v[68:69] op_sel_hi:[1,0]
	v_pk_mul_f32 v[32:33], v[32:33], v[68:69] op_sel_hi:[1,0]
	v_pk_mul_f32 v[30:31], v[30:31], v[68:69] op_sel_hi:[1,0]
	v_pk_mul_f32 v[28:29], v[28:29], v[68:69] op_sel_hi:[1,0]
	v_pk_mul_f32 v[26:27], v[26:27], v[68:69] op_sel_hi:[1,0]
	v_pk_mul_f32 v[24:25], v[24:25], v[68:69] op_sel_hi:[1,0]
	v_pk_mul_f32 v[22:23], v[22:23], v[68:69] op_sel_hi:[1,0]
	v_pk_mul_f32 v[20:21], v[20:21], v[68:69] op_sel_hi:[1,0]
	v_pk_mul_f32 v[18:19], v[18:19], v[68:69] op_sel_hi:[1,0]
	v_pk_mul_f32 v[48:49], v[48:49], v[68:69] op_sel_hi:[1,0]
	v_pk_mul_f32 v[46:47], v[46:47], v[68:69] op_sel_hi:[1,0]
	v_pk_mul_f32 v[44:45], v[44:45], v[68:69] op_sel_hi:[1,0]
	v_pk_mul_f32 v[42:43], v[42:43], v[68:69] op_sel_hi:[1,0]
	v_pk_mul_f32 v[40:41], v[40:41], v[68:69] op_sel_hi:[1,0]
	v_pk_mul_f32 v[38:39], v[38:39], v[68:69] op_sel_hi:[1,0]
	v_pk_mul_f32 v[36:37], v[36:37], v[68:69] op_sel_hi:[1,0]
	v_pk_mul_f32 v[34:35], v[34:35], v[68:69] op_sel_hi:[1,0]
	v_pk_mul_f32 v[64:65], v[64:65], v[68:69] op_sel_hi:[1,0]
	v_pk_mul_f32 v[62:63], v[62:63], v[68:69] op_sel_hi:[1,0]
	v_pk_mul_f32 v[60:61], v[60:61], v[68:69] op_sel_hi:[1,0]
	v_pk_mul_f32 v[58:59], v[58:59], v[68:69] op_sel_hi:[1,0]
	v_pk_mul_f32 v[56:57], v[56:57], v[68:69] op_sel_hi:[1,0]
	v_pk_mul_f32 v[54:55], v[54:55], v[68:69] op_sel_hi:[1,0]
	v_pk_mul_f32 v[52:53], v[52:53], v[68:69] op_sel_hi:[1,0]
	v_pk_mul_f32 v[50:51], v[50:51], v[68:69] op_sel_hi:[1,0]
	v_sub_f32_e32 v150, v150, v67
	v_sub_f32_e32 v151, v151, v67
	v_sub_f32_e32 v152, v152, v67
	v_sub_f32_e32 v153, v153, v67
	v_sub_f32_e32 v154, v154, v67
	v_sub_f32_e32 v155, v155, v67
	v_sub_f32_e32 v156, v156, v67
	v_sub_f32_e32 v157, v157, v67
	v_sub_f32_e32 v104, v104, v67
	v_sub_f32_e32 v105, v105, v67
	v_sub_f32_e32 v106, v106, v67
	v_sub_f32_e32 v107, v107, v67
	v_sub_f32_e32 v92, v92, v67
	v_sub_f32_e32 v93, v93, v67
	v_sub_f32_e32 v94, v94, v67
	v_sub_f32_e32 v95, v95, v67
	v_mul_f32_e32 v158, v158, v68
	v_mov_b32_e32 v67, v66
	v_mov_b32_e32 v68, v66
	v_mov_b32_e32 v69, v66
	v_mov_b32_e32 v70, v66
	v_mov_b32_e32 v71, v66
	v_mov_b32_e32 v72, v66
	v_mov_b32_e32 v73, v66
	v_mov_b32_e32 v74, v66
	v_mov_b32_e32 v75, v66
	v_mov_b32_e32 v76, v66
	v_mov_b32_e32 v77, v66
	v_mov_b32_e32 v78, v66
	v_mov_b32_e32 v79, v66
	v_mov_b32_e32 v80, v66
	v_mov_b32_e32 v81, v66
	s_branch .LBB0_587
